# attention tiles: dropped 4 dead v_readlane per tile (s4-s7 are rewritten before any use)
# speedup vs baseline: 1.0014x; 1.0003x over previous
.LBB0_462:
	s_setprio 1
	ds_read_b128 v[160:163], v104 offset:0
	ds_read_b128 v[164:167], v104 offset:3328
	ds_read_b128 v[168:171], v104 offset:6656
	ds_read_b128 v[172:175], v104 offset:9984
	ds_read_b128 v[224:227], v104 offset:64
	ds_read_b128 v[228:231], v104 offset:3392
	ds_read_b128 v[232:235], v104 offset:6720
	ds_read_b128 v[236:239], v104 offset:10048
	s_waitcnt lgkmcnt(6)
	v_mfma_f32_16x16x32_bf16 v[124:127], v[160:163], v[0:3], -4.0
	v_mfma_f32_16x16x32_bf16 v[128:131], v[160:163], v[12:15], -4.0
	ds_read_b128 v[160:163], v104 offset:128
	v_mfma_f32_16x16x32_bf16 v[132:135], v[164:167], v[0:3], -4.0
	v_mfma_f32_16x16x32_bf16 v[136:139], v[164:167], v[12:15], -4.0
	ds_read_b128 v[164:167], v104 offset:3456
	s_waitcnt lgkmcnt(6)
	v_mfma_f32_16x16x32_bf16 v[140:143], v[168:171], v[0:3], -4.0
	v_mfma_f32_16x16x32_bf16 v[144:147], v[168:171], v[12:15], -4.0
	ds_read_b128 v[168:171], v104 offset:6784
	v_mfma_f32_16x16x32_bf16 v[148:151], v[172:175], v[0:3], -4.0
	v_mfma_f32_16x16x32_bf16 v[152:155], v[172:175], v[12:15], -4.0
	ds_read_b128 v[172:175], v104 offset:10112
	s_waitcnt lgkmcnt(6)
	v_mfma_f32_16x16x32_bf16 v[124:127], v[224:227], v[4:7], v[124:127]
	v_mfma_f32_16x16x32_bf16 v[128:131], v[224:227], v[16:19], v[128:131]
	ds_read_b64 v[224:225], v219 offset:13312
	ds_read_b64 v[226:227], v219 offset:13344
	v_mfma_f32_16x16x32_bf16 v[132:135], v[228:231], v[4:7], v[132:135]
	v_mfma_f32_16x16x32_bf16 v[136:139], v[228:231], v[16:19], v[136:139]
	ds_read_b64 v[228:229], v219 offset:15616
	ds_read_b64 v[230:231], v219 offset:15648
	s_waitcnt lgkmcnt(8)
	v_mfma_f32_16x16x32_bf16 v[140:143], v[232:235], v[4:7], v[140:143]
	v_mfma_f32_16x16x32_bf16 v[144:147], v[232:235], v[16:19], v[144:147]
	ds_read_b64 v[232:233], v219 offset:17920
	ds_read_b64 v[234:235], v219 offset:17952
	v_mfma_f32_16x16x32_bf16 v[148:151], v[236:239], v[4:7], v[148:151]
	v_mfma_f32_16x16x32_bf16 v[152:155], v[236:239], v[16:19], v[152:155]
	ds_read_b64 v[236:237], v219 offset:20224
	ds_read_b64 v[238:239], v219 offset:20256
	s_waitcnt lgkmcnt(10)
	v_mfma_f32_16x16x32_bf16 v[124:127], v[160:163], v[8:11], v[124:127]
	v_mfma_f32_16x16x32_bf16 v[128:131], v[160:163], v[20:23], v[128:131]
	ds_read_b64 v[160:161], v219 offset:13376
	ds_read_b64 v[162:163], v219 offset:13408
	v_mfma_f32_16x16x32_bf16 v[132:135], v[164:167], v[8:11], v[132:135]
	v_mfma_f32_16x16x32_bf16 v[136:139], v[164:167], v[20:23], v[136:139]
	ds_read_b64 v[164:165], v219 offset:15680
	ds_read_b64 v[166:167], v219 offset:15712
	s_waitcnt lgkmcnt(12)
	v_mfma_f32_16x16x32_bf16 v[140:143], v[168:171], v[8:11], v[140:143]
	v_mfma_f32_16x16x32_bf16 v[144:147], v[168:171], v[20:23], v[144:147]
	ds_read_b64 v[168:169], v219 offset:17984
	ds_read_b64 v[170:171], v219 offset:18016
	v_mfma_f32_16x16x32_bf16 v[148:151], v[172:175], v[8:11], v[148:151]
	v_mfma_f32_16x16x32_bf16 v[152:155], v[172:175], v[20:23], v[152:155]
	ds_read_b64 v[172:173], v219 offset:20288
	ds_read_b64 v[174:175], v219 offset:20320
	s_setprio 0
	v_exp_f32_e32 v124, v124
	v_exp_f32_e32 v125, v125
	v_exp_f32_e32 v126, v126
	v_exp_f32_e32 v127, v127
	v_add_f32_e32 v118, v118, v124
	v_add_f32_e32 v119, v119, v125
	v_exp_f32_e32 v128, v128
	v_exp_f32_e32 v129, v129
	v_add_f32_e32 v118, v118, v126
	v_add_f32_e32 v119, v119, v127
	v_exp_f32_e32 v130, v130
	v_exp_f32_e32 v131, v131
	v_add_f32_e32 v176, v176, v128
	v_add_f32_e32 v177, v177, v129
	v_exp_f32_e32 v132, v132
	v_exp_f32_e32 v133, v133
	v_add_f32_e32 v176, v176, v130
	v_add_f32_e32 v177, v177, v131
	v_exp_f32_e32 v134, v134
	v_exp_f32_e32 v135, v135
	v_add_f32_e32 v118, v118, v132
	v_add_f32_e32 v119, v119, v133
	v_exp_f32_e32 v136, v136
	v_exp_f32_e32 v137, v137
	v_add_f32_e32 v118, v118, v134
	v_add_f32_e32 v119, v119, v135
	v_exp_f32_e32 v138, v138
	v_exp_f32_e32 v139, v139
	v_add_f32_e32 v176, v176, v136
	v_add_f32_e32 v177, v177, v137
	v_cvt_pk_bf16_f32 v240, v124, v125
	v_add_f32_e32 v176, v176, v138
	v_add_f32_e32 v177, v177, v139
	v_cvt_pk_bf16_f32 v241, v126, v127
	v_cvt_pk_bf16_f32 v242, v132, v133
	v_cvt_pk_bf16_f32 v243, v134, v135
	v_cvt_pk_bf16_f32 v244, v128, v129
	v_cvt_pk_bf16_f32 v245, v130, v131
	v_cvt_pk_bf16_f32 v246, v136, v137
	v_cvt_pk_bf16_f32 v247, v138, v139
	s_waitcnt lgkmcnt(12)
	v_mfma_f32_16x16x32_bf16 v[92:95], v[224:227], v[240:243], v[92:95]
	v_exp_f32_e32 v140, v140
	v_exp_f32_e32 v141, v141
	v_exp_f32_e32 v142, v142
	v_exp_f32_e32 v143, v143
	v_add_f32_e32 v118, v118, v140
	v_mfma_f32_16x16x32_bf16 v[84:87], v[224:227], v[244:247], v[84:87]
	v_add_f32_e32 v119, v119, v141
	v_exp_f32_e32 v144, v144
	v_exp_f32_e32 v145, v145
	v_add_f32_e32 v118, v118, v142
	v_add_f32_e32 v119, v119, v143
	v_mfma_f32_16x16x32_bf16 v[88:91], v[228:231], v[240:243], v[88:91]
	v_exp_f32_e32 v146, v146
	v_exp_f32_e32 v147, v147
	v_add_f32_e32 v176, v176, v144
	v_add_f32_e32 v177, v177, v145
	v_exp_f32_e32 v148, v148
	v_mfma_f32_16x16x32_bf16 v[76:79], v[228:231], v[244:247], v[76:79]
	v_exp_f32_e32 v149, v149
	v_add_f32_e32 v176, v176, v146
	v_add_f32_e32 v177, v177, v147
	v_exp_f32_e32 v150, v150
	v_exp_f32_e32 v151, v151
	s_waitcnt lgkmcnt(8)
	v_mfma_f32_16x16x32_bf16 v[80:83], v[232:235], v[240:243], v[80:83]
	v_add_f32_e32 v118, v118, v148
	v_add_f32_e32 v119, v119, v149
	v_exp_f32_e32 v152, v152
	v_exp_f32_e32 v153, v153
	v_add_f32_e32 v118, v118, v150
	v_mfma_f32_16x16x32_bf16 v[68:71], v[232:235], v[244:247], v[68:71]
	v_add_f32_e32 v119, v119, v151
	v_exp_f32_e32 v154, v154
	v_exp_f32_e32 v155, v155
	v_add_f32_e32 v176, v176, v152
	v_add_f32_e32 v177, v177, v153
	v_mfma_f32_16x16x32_bf16 v[72:75], v[236:239], v[240:243], v[72:75]
	v_cvt_pk_bf16_f32 v96, v140, v141
	v_add_f32_e32 v176, v176, v154
	v_add_f32_e32 v177, v177, v155
	v_cvt_pk_bf16_f32 v97, v142, v143
	v_cvt_pk_bf16_f32 v98, v148, v149
	v_mfma_f32_16x16x32_bf16 v[64:67], v[236:239], v[244:247], v[64:67]
	v_cvt_pk_bf16_f32 v99, v150, v151
	v_cvt_pk_bf16_f32 v100, v144, v145
	v_cvt_pk_bf16_f32 v101, v146, v147
	v_cvt_pk_bf16_f32 v102, v152, v153
	v_cvt_pk_bf16_f32 v103, v154, v155
	s_nop 1
	s_waitcnt lgkmcnt(4)
	v_mfma_f32_16x16x32_bf16 v[92:95], v[160:163], v[96:99], v[92:95]
	v_mfma_f32_16x16x32_bf16 v[84:87], v[160:163], v[100:103], v[84:87]
	v_mfma_f32_16x16x32_bf16 v[88:91], v[164:167], v[96:99], v[88:91]
	v_mfma_f32_16x16x32_bf16 v[76:79], v[164:167], v[100:103], v[76:79]
	s_waitcnt lgkmcnt(0)
	v_mfma_f32_16x16x32_bf16 v[80:83], v[168:171], v[96:99], v[80:83]
	v_mfma_f32_16x16x32_bf16 v[68:71], v[168:171], v[100:103], v[68:71]
	v_mfma_f32_16x16x32_bf16 v[72:75], v[172:175], v[96:99], v[72:75]
	v_mfma_f32_16x16x32_bf16 v[64:67], v[172:175], v[100:103], v[64:67]
	s_add_i32 s44, s42, -2
	s_cmp_ge_u32 s44, s35
	s_cbranch_scc1 .LBB0_464
	s_waitcnt vmcnt(4)
	ds_write_b128 v115, v[24:27] offset:22528
	s_waitcnt vmcnt(3)
	ds_write_b128 v117, v[28:31] offset:22528
	s_waitcnt vmcnt(1)
	ds_write_b128 v217, v[36:39] offset:22528
	ds_write_b128 v218, v[32:35] offset:35840
	s_waitcnt vmcnt(0)
	ds_write_b128 v218, v[40:43] offset:40448

.LBB0_466:
	s_setprio 1
	ds_read_b128 v[160:163], v104 offset:22528
	ds_read_b128 v[164:167], v104 offset:25856
	ds_read_b128 v[168:171], v104 offset:29184
	ds_read_b128 v[172:175], v104 offset:32512
	ds_read_b128 v[224:227], v104 offset:22592
	ds_read_b128 v[228:231], v104 offset:25920
	ds_read_b128 v[232:235], v104 offset:29248
	ds_read_b128 v[236:239], v104 offset:32576
	s_waitcnt lgkmcnt(6)
	v_mfma_f32_16x16x32_bf16 v[124:127], v[160:163], v[0:3], -4.0
	v_mfma_f32_16x16x32_bf16 v[128:131], v[160:163], v[12:15], -4.0
	ds_read_b128 v[160:163], v104 offset:22656
	v_mfma_f32_16x16x32_bf16 v[132:135], v[164:167], v[0:3], -4.0
	v_mfma_f32_16x16x32_bf16 v[136:139], v[164:167], v[12:15], -4.0
	ds_read_b128 v[164:167], v104 offset:25984
	s_waitcnt lgkmcnt(6)
	v_mfma_f32_16x16x32_bf16 v[140:143], v[168:171], v[0:3], -4.0
	v_mfma_f32_16x16x32_bf16 v[144:147], v[168:171], v[12:15], -4.0
	ds_read_b128 v[168:171], v104 offset:29312
	v_mfma_f32_16x16x32_bf16 v[148:151], v[172:175], v[0:3], -4.0
	v_mfma_f32_16x16x32_bf16 v[152:155], v[172:175], v[12:15], -4.0
	ds_read_b128 v[172:175], v104 offset:32640
	s_waitcnt lgkmcnt(6)
	v_mfma_f32_16x16x32_bf16 v[124:127], v[224:227], v[4:7], v[124:127]
	v_mfma_f32_16x16x32_bf16 v[128:131], v[224:227], v[16:19], v[128:131]
	ds_read_b64 v[224:225], v219 offset:35840
	ds_read_b64 v[226:227], v219 offset:35872
	v_mfma_f32_16x16x32_bf16 v[132:135], v[228:231], v[4:7], v[132:135]
	v_mfma_f32_16x16x32_bf16 v[136:139], v[228:231], v[16:19], v[136:139]
	ds_read_b64 v[228:229], v219 offset:38144
	ds_read_b64 v[230:231], v219 offset:38176
	s_waitcnt lgkmcnt(8)
	v_mfma_f32_16x16x32_bf16 v[140:143], v[232:235], v[4:7], v[140:143]
	v_mfma_f32_16x16x32_bf16 v[144:147], v[232:235], v[16:19], v[144:147]
	ds_read_b64 v[232:233], v219 offset:40448
	ds_read_b64 v[234:235], v219 offset:40480
	v_mfma_f32_16x16x32_bf16 v[148:151], v[236:239], v[4:7], v[148:151]
	v_mfma_f32_16x16x32_bf16 v[152:155], v[236:239], v[16:19], v[152:155]
	ds_read_b64 v[236:237], v219 offset:42752
	ds_read_b64 v[238:239], v219 offset:42784
	s_waitcnt lgkmcnt(10)
	v_mfma_f32_16x16x32_bf16 v[124:127], v[160:163], v[8:11], v[124:127]
	v_mfma_f32_16x16x32_bf16 v[128:131], v[160:163], v[20:23], v[128:131]
	ds_read_b64 v[160:161], v219 offset:35904
	ds_read_b64 v[162:163], v219 offset:35936
	v_mfma_f32_16x16x32_bf16 v[132:135], v[164:167], v[8:11], v[132:135]
	v_mfma_f32_16x16x32_bf16 v[136:139], v[164:167], v[20:23], v[136:139]
	ds_read_b64 v[164:165], v219 offset:38208
	ds_read_b64 v[166:167], v219 offset:38240
	s_waitcnt lgkmcnt(12)
	v_mfma_f32_16x16x32_bf16 v[140:143], v[168:171], v[8:11], v[140:143]
	v_mfma_f32_16x16x32_bf16 v[144:147], v[168:171], v[20:23], v[144:147]
	ds_read_b64 v[168:169], v219 offset:40512
	ds_read_b64 v[170:171], v219 offset:40544
	v_mfma_f32_16x16x32_bf16 v[148:151], v[172:175], v[8:11], v[148:151]
	v_mfma_f32_16x16x32_bf16 v[152:155], v[172:175], v[20:23], v[152:155]
	ds_read_b64 v[172:173], v219 offset:42816
	ds_read_b64 v[174:175], v219 offset:42848
	s_setprio 0
	v_exp_f32_e32 v124, v124
	v_exp_f32_e32 v125, v125
	v_exp_f32_e32 v126, v126
	v_exp_f32_e32 v127, v127
	v_add_f32_e32 v118, v118, v124
	v_add_f32_e32 v119, v119, v125
	v_exp_f32_e32 v128, v128
	v_exp_f32_e32 v129, v129
	v_add_f32_e32 v118, v118, v126
	v_add_f32_e32 v119, v119, v127
	v_exp_f32_e32 v130, v130
	v_exp_f32_e32 v131, v131
	v_add_f32_e32 v176, v176, v128
	v_add_f32_e32 v177, v177, v129
	v_exp_f32_e32 v132, v132
	v_exp_f32_e32 v133, v133
	v_add_f32_e32 v176, v176, v130
	v_add_f32_e32 v177, v177, v131
	v_exp_f32_e32 v134, v134
	v_exp_f32_e32 v135, v135
	v_add_f32_e32 v118, v118, v132
	v_add_f32_e32 v119, v119, v133
	v_exp_f32_e32 v136, v136
	v_exp_f32_e32 v137, v137
	v_add_f32_e32 v118, v118, v134
	v_add_f32_e32 v119, v119, v135
	v_exp_f32_e32 v138, v138
	v_exp_f32_e32 v139, v139
	v_add_f32_e32 v176, v176, v136
	v_add_f32_e32 v177, v177, v137
	v_cvt_pk_bf16_f32 v240, v124, v125
	v_add_f32_e32 v176, v176, v138
	v_add_f32_e32 v177, v177, v139
	v_cvt_pk_bf16_f32 v241, v126, v127
	v_cvt_pk_bf16_f32 v242, v132, v133
	v_cvt_pk_bf16_f32 v243, v134, v135
	v_cvt_pk_bf16_f32 v244, v128, v129
	v_cvt_pk_bf16_f32 v245, v130, v131
	v_cvt_pk_bf16_f32 v246, v136, v137
	v_cvt_pk_bf16_f32 v247, v138, v139
	s_waitcnt lgkmcnt(12)
	v_mfma_f32_16x16x32_bf16 v[92:95], v[224:227], v[240:243], v[92:95]
	v_exp_f32_e32 v140, v140
	v_exp_f32_e32 v141, v141
	v_exp_f32_e32 v142, v142
	v_exp_f32_e32 v143, v143
	v_add_f32_e32 v118, v118, v140
	v_mfma_f32_16x16x32_bf16 v[84:87], v[224:227], v[244:247], v[84:87]
	v_add_f32_e32 v119, v119, v141
	v_exp_f32_e32 v144, v144
	v_exp_f32_e32 v145, v145
	v_add_f32_e32 v118, v118, v142
	v_add_f32_e32 v119, v119, v143
	v_mfma_f32_16x16x32_bf16 v[88:91], v[228:231], v[240:243], v[88:91]
	v_exp_f32_e32 v146, v146
	v_exp_f32_e32 v147, v147
	v_add_f32_e32 v176, v176, v144
	v_add_f32_e32 v177, v177, v145
	v_exp_f32_e32 v148, v148
	v_mfma_f32_16x16x32_bf16 v[76:79], v[228:231], v[244:247], v[76:79]
	v_exp_f32_e32 v149, v149
	v_add_f32_e32 v176, v176, v146
	v_add_f32_e32 v177, v177, v147
	v_exp_f32_e32 v150, v150
	v_exp_f32_e32 v151, v151
	s_waitcnt lgkmcnt(8)
	v_mfma_f32_16x16x32_bf16 v[80:83], v[232:235], v[240:243], v[80:83]
	v_add_f32_e32 v118, v118, v148
	v_add_f32_e32 v119, v119, v149
	v_exp_f32_e32 v152, v152
	v_exp_f32_e32 v153, v153
	v_add_f32_e32 v118, v118, v150
	v_mfma_f32_16x16x32_bf16 v[68:71], v[232:235], v[244:247], v[68:71]
	v_add_f32_e32 v119, v119, v151
	v_exp_f32_e32 v154, v154
	v_exp_f32_e32 v155, v155
	v_add_f32_e32 v176, v176, v152
	v_add_f32_e32 v177, v177, v153
	v_mfma_f32_16x16x32_bf16 v[72:75], v[236:239], v[240:243], v[72:75]
	v_cvt_pk_bf16_f32 v96, v140, v141
	v_add_f32_e32 v176, v176, v154
	v_add_f32_e32 v177, v177, v155
	v_cvt_pk_bf16_f32 v97, v142, v143
	v_cvt_pk_bf16_f32 v98, v148, v149
	v_mfma_f32_16x16x32_bf16 v[64:67], v[236:239], v[244:247], v[64:67]
	v_cvt_pk_bf16_f32 v99, v150, v151
	v_cvt_pk_bf16_f32 v100, v144, v145
	v_cvt_pk_bf16_f32 v101, v146, v147
	v_cvt_pk_bf16_f32 v102, v152, v153
	v_cvt_pk_bf16_f32 v103, v154, v155
	s_nop 1
	s_waitcnt lgkmcnt(4)
	v_mfma_f32_16x16x32_bf16 v[92:95], v[160:163], v[96:99], v[92:95]
	v_mfma_f32_16x16x32_bf16 v[84:87], v[160:163], v[100:103], v[84:87]
	v_mfma_f32_16x16x32_bf16 v[88:91], v[164:167], v[96:99], v[88:91]
	v_mfma_f32_16x16x32_bf16 v[76:79], v[164:167], v[100:103], v[76:79]
	s_waitcnt lgkmcnt(0)
	v_mfma_f32_16x16x32_bf16 v[80:83], v[168:171], v[96:99], v[80:83]
	v_mfma_f32_16x16x32_bf16 v[68:71], v[168:171], v[100:103], v[68:71]
	v_mfma_f32_16x16x32_bf16 v[72:75], v[172:175], v[96:99], v[72:75]
	v_mfma_f32_16x16x32_bf16 v[64:67], v[172:175], v[100:103], v[64:67]
	s_andn2_b64 vcc, exec, s[0:1]
	s_cbranch_vccnz .LBB0_459
	s_waitcnt vmcnt(4)
	ds_write_b128 v115, v[44:47]
	s_waitcnt vmcnt(3)
	ds_write_b128 v117, v[48:51]
	s_waitcnt vmcnt(2)
	ds_write_b128 v217, v[52:55]
	s_waitcnt vmcnt(1)
	ds_write_b128 v218, v[56:59] offset:13312
	s_waitcnt vmcnt(0)
	ds_write_b128 v218, v[60:63] offset:17920
	s_branch .LBB0_459
